# RWKV scan state-dependent stage: the four state-update groups overlapped (all BKT/decay reads issued up front, MFMA accumulates onto S directly) and MAT/TT/imgR LDS reads hoisted to the chunk top with
# speedup vs baseline: 1.0362x; 1.0071x over previous
; __device__ __forceinline__ void scan_item(const Params& p, int stream, int h, unsigned char* smem) {
;     ...
; #pragma unroll
;         for (int ks = 0; ks < 2; ++ks) {
;           w = (u32x4){pack2(S[2 * ks][0], S[2 * ks][1]), pack2(S[2 * ks][2], S[2 * ks][3]),
;                       pack2(S[2 * ks + 1][0], S[2 * ks + 1][1]), pack2(S[2 * ks + 1][2], S[2 * ks + 1][3])};
;           sfr[ks] = __builtin_bit_cast(bf16x8, w);
;         }
;         float vv[4];
; #pragma unroll
;         for (int e = 0; e < 4; ++e) vv[e] = c_V[(4 * q + e) * 64 + vme];
;         const u32x2 vpk = {pack2(vv[0], vv[1]), pack2(vv[2], vv[3])};
;         f32x4 rhs = {0.f, 0.f, 0.f, 0.f};
; #pragma unroll
;         for (int ks = 0; ks < 2; ++ks) {
;           u32x2 lo = *(const u32x2*)(c_imgA + r * 144 + (32 * ks + 4 * q) * 2);
;           u32x2 hi = *(const u32x2*)(c_imgA + r * 144 + (32 * ks + 16 + 4 * q) * 2);
;           w = (u32x4){lo[0], lo[1], hi[0], hi[1]};
;           rhs = mfma16(__builtin_bit_cast(bf16x8, w), sfr[ks], rhs);
;         }
;         {
;           u32x2 nk = *(const u32x2*)(c_MAT + 1 * 640 + r * 40 + q * 8);
;           w = (u32x4){nk[0], nk[1], 0u, 0u};
;           u32x4 wb = {vpk[0], vpk[1], 0u, 0u};
;           rhs = mfma16(__builtin_bit_cast(bf16x8, w), __builtin_bit_cast(bf16x8, wb), rhs);
;         }
;         f32x4 ut = {0.f, 0.f, 0.f, 0.f};
;         {
;           u32x2 tv = *(const u32x2*)(c_TT + r * 40 + q * 8);
;           w = (u32x4){tv[0], tv[1], 0u, 0u};
;           u32x4 wb = {pack2(rhs[0], rhs[1]), pack2(rhs[2], rhs[3]), 0u, 0u};
;           ut = mfma16(__builtin_bit_cast(bf16x8, w), __builtin_bit_cast(bf16x8, wb), ut);
;         }
;         const u32x4 uvb = {pack2(ut[0], ut[1]), pack2(ut[2], ut[3]), vpk[0], vpk[1]};
;         const bf16x8 uvf = __builtin_bit_cast(bf16x8, uvb);
;         f32x4 yt = {0.f, 0.f, 0.f, 0.f};
; #pragma unroll
;         for (int ks = 0; ks < 2; ++ks) {
;           u32x2 lo = *(const u32x2*)(c_imgR + r * 144 + (32 * ks + 4 * q) * 2);
;           u32x2 hi = *(const u32x2*)(c_imgR + r * 144 + (32 * ks + 16 + 4 * q) * 2);
;           w = (u32x4){lo[0], lo[1], hi[0], hi[1]};
;           yt = mfma16(__builtin_bit_cast(bf16x8, w), sfr[ks], yt);
;         }
;         {
;           u32x2 mb = *(const u32x2*)(c_MAT + 2 * 640 + r * 40 + q * 8);
;           u32x2 mk = *(const u32x2*)(c_MAT + 3 * 640 + r * 40 + q * 8);
.LBB0_1606:
	v_lshlrev_b32_e32 v0, 2, v194
	v_add3_u32 v150, s75, v203, v0
	ds_read2st64_b32 v[0:1], v150 offset0:80 offset1:81
	ds_read2st64_b32 v[78:79], v150 offset0:82 offset1:83
	v_add3_u32 v88, s75, v200, v95
	v_cvt_pk_bf16_f32 v68, v36, v37
	v_cvt_pk_bf16_f32 v69, v38, v39
	s_waitcnt lgkmcnt(1)
	v_cvt_pk_bf16_f32 v76, v0, v1
	v_add_u32_e32 v0, 0xa000, v88
	s_waitcnt lgkmcnt(0)
	v_cvt_pk_bf16_f32 v77, v78, v79
	ds_read2_b64 v[78:81], v0 offset0:32 offset1:36
	ds_read2_b64 v[82:85], v0 offset0:40 offset1:44
	v_add3_u32 v89, s75, v201, v95
	v_add_u32_e32 v238, 0xd800, v89
	v_add_u32_e32 v239, 0xde80, v89
	v_add_u32_e32 v88, 0xa800, v88
	ds_read2_b64 v[240:243], v238 offset0:48 offset1:128
	ds_read2_b64 v[244:247], v239 offset1:240
	ds_read2_b64 v[248:251], v88 offset0:64 offset1:68
	ds_read2_b64 v[252:255], v88 offset0:72 offset1:76
	v_cvt_pk_bf16_f32 v70, v40, v41
	v_cvt_pk_bf16_f32 v71, v42, v43
	v_cvt_pk_bf16_f32 v72, v44, v45
	v_cvt_pk_bf16_f32 v73, v46, v47
	s_waitcnt lgkmcnt(5)
	v_mfma_f32_16x16x32_bf16 v[78:81], v[78:81], v[68:71], 0
	v_cvt_pk_bf16_f32 v74, v48, v49
	v_cvt_pk_bf16_f32 v75, v50, v51
	v_mov_b32_e32 v3, v2
	s_waitcnt lgkmcnt(4)
	v_mfma_f32_16x16x32_bf16 v[80:83], v[82:85], v[72:75], v[78:81]
	s_xor_b64 s[66:67], s[66:67], -1
	s_waitcnt lgkmcnt(3)
	v_mov_b32_e32 v0, v240
	v_mov_b32_e32 v1, v241
	v_mov_b32_e32 v78, v2
	v_mov_b32_e32 v79, v2
	s_nop 1
	v_mfma_f32_16x16x32_bf16 v[78:81], v[0:3], v[76:79], v[80:83]
	s_nop 1
	s_waitcnt lgkmcnt(2)
	v_mov_b32_e32 v0, v246
	v_mov_b32_e32 v1, v247
	s_nop 2
	v_cvt_pk_bf16_f32 v78, v78, v79
	v_cvt_pk_bf16_f32 v79, v80, v81
	v_mov_b32_e32 v80, v2
	v_mov_b32_e32 v81, v2
	s_nop 1
	v_mfma_f32_16x16x32_bf16 v[78:81], v[0:3], v[78:81], 0
	v_add_u32_e32 v3, s75, v92
	s_waitcnt lgkmcnt(1)
	v_mfma_f32_16x16x32_bf16 v[68:71], v[248:251], v[68:71], 0
	s_nop 4
	v_cvt_pk_bf16_f32 v78, v78, v79
	v_cvt_pk_bf16_f32 v79, v80, v81
	s_waitcnt lgkmcnt(0)
	v_mfma_f32_16x16x32_bf16 v[68:71], v[252:255], v[72:75], v[68:71]
	v_mov_b32_e32 v72, v242
	v_mov_b32_e32 v73, v243
	v_mov_b32_e32 v74, v244
	v_mov_b32_e32 v75, v245
	v_mov_b32_e32 v80, v76
	v_mov_b32_e32 v81, v77
	v_add3_u32 v76, s75, v218, v95
	v_add_u32_e32 v0, 0xc000, v76
	v_mfma_f32_16x16x32_bf16 v[68:71], v[72:75], v[78:81], v[68:71]
	s_nop 7
	ds_write2st64_b32 v150, v68, v69 offset0:112 offset1:113
	ds_write2st64_b32 v150, v70, v71 offset0:114 offset1:115
	v_add_u32_e32 v77, 0xc800, v76
	v_add_u32_e32 v238, 0xd000, v76
	ds_read2_b64 v[240:243], v0 offset0:160 offset1:164
	ds_read2_b64 v[244:247], v77 offset0:48 offset1:52
	ds_read2_b64 v[248:251], v77 offset0:192 offset1:196
	ds_read2_b64 v[68:71], v238 offset0:80 offset1:84
	ds_read_b128 v[72:75], v3 offset:58624
	s_waitcnt lgkmcnt(4)
	v_mfma_f32_16x16x32_bf16 v[36:39], v[240:243], v[78:81], v[36:39]
	s_waitcnt lgkmcnt(3)
	v_mfma_f32_16x16x32_bf16 v[40:43], v[244:247], v[78:81], v[40:43]
	s_waitcnt lgkmcnt(2)
	v_mfma_f32_16x16x32_bf16 v[44:47], v[248:251], v[78:81], v[44:47]
	s_waitcnt lgkmcnt(1)
	v_mfma_f32_16x16x32_bf16 v[48:51], v[68:71], v[78:81], v[48:51]
	ds_read_b128 v[240:243], v3 offset:58688
	ds_read_b128 v[244:247], v3 offset:58752
	ds_read_b128 v[248:251], v3 offset:58816
	s_waitcnt lgkmcnt(3)
	s_nop 1
	v_pk_mul_f32 v[36:37], v[72:73], v[36:37]
	v_pk_mul_f32 v[38:39], v[38:39], v[74:75]
	s_waitcnt lgkmcnt(2)
	v_pk_mul_f32 v[40:41], v[240:241], v[40:41]
	v_pk_mul_f32 v[42:43], v[42:43], v[242:243]
	s_waitcnt lgkmcnt(1)
	v_pk_mul_f32 v[44:45], v[244:245], v[44:45]
	v_pk_mul_f32 v[46:47], v[46:47], v[246:247]
	s_waitcnt lgkmcnt(0)
	s_nop 3
	v_pk_mul_f32 v[48:49], v[248:249], v[48:49]
	v_pk_mul_f32 v[50:51], v[50:51], v[250:251]
	s_mov_b32 s75, 0xf000
	s_andn2_b64 vcc, exec, s[66:67]
	s_mov_b64 s[66:67], 0
	s_cbranch_vccz .LBB0_1608
	s_mov_b64 s[70:71], s[34:35]
	s_andn2_b64 vcc, exec, s[70:71]
	s_cbranch_vccnz .LBB0_1605
	s_branch .LBB0_1606
